# diff-attention P.V block: first VALU->MFMA operand wait filled with two next-slice fmamk instead of s_nop 1
# baseline (speedup 1.0000x reference)
; __device__ __forceinline__ unsigned cvtpk(float lo, float hi) { f32x2_t v = {lo, hi}; bf16x2_t b = __builtin_convertvector(v, bf16x2_t); return __builtin_bit_cast(unsigned, b); }
; #define ATT_MMAG(F, dvb) do { _Pragma("unroll") for (int j = 0; j < 4; ++j) o[dvb] = __builtin_amdgcn_mfma_f32_32x32x16_bf16(F[j], pb[j >> 1][j & 1], o[dvb], 0, 0, 0); } while (0)
; template <bool DIFF> ...
;     ...
;             const float d0 = c0 - m_run, d1 = c1 - m_run;
;             float rs0 = 0.f, rs1 = 0.f;
; #pragma unroll
;             for (int r = 0; r < 16; ++r) { s0[r] = __builtin_amdgcn_exp2f(__builtin_fmaf(s0[r], sc2, d0)); s1[r] = __builtin_amdgcn_exp2f(__builtin_fmaf(s1[r], sc2, d1)); rs0 += s0[r]; rs1 += s1[r]; }
;             l_run += rs0 + rs1;
;             bf16x8 pb[2][2];
; #pragma unroll
;             for (int g = 0; g < 2; ++g) {
;                 u32x4 w0, w1;
;                 w0.x = cvtpk(s0[8 * g], s0[8 * g + 1]); w0.y = cvtpk(s0[8 * g + 2], s0[8 * g + 3]); w0.z = cvtpk(s0[8 * g + 4], s0[8 * g + 5]); w0.w = cvtpk(s0[8 * g + 6], s0[8 * g + 7]);
;                 w1.x = cvtpk(s1[8 * g], s1[8 * g + 1]); w1.y = cvtpk(s1[8 * g + 2], s1[8 * g + 3]); w1.z = cvtpk(s1[8 * g + 4], s1[8 * g + 5]); w1.w = cvtpk(s1[8 * g + 6], s1[8 * g + 7]);
;                 pb[0][g] = __builtin_bit_cast(bf16x8, w0); pb[1][g] = __builtin_bit_cast(bf16x8, w1);
;             }
;             __builtin_amdgcn_sched_barrier(0);
;             ATT_MMAG(fa, 0); ATT_LOADG(fa, 2); __builtin_amdgcn_sched_barrier(0); ATT_MMAG(fb, 1); ATT_LOADG(fb, 3); __builtin_amdgcn_sched_barrier(0); ATT_MMAG(fa, 2); ATT_MMAG(fb, 3);
.LBB0_112:
	v_sub_f32_e32 v227, v213, v209
	v_sub_f32_e32 v226, v212, v209
	v_fmamk_f32 v98, v98, 0x3e38aa3b, v226
	v_fmamk_f32 v99, v99, 0x3e38aa3b, v226
	v_fmamk_f32 v100, v100, 0x3e38aa3b, v226
	v_fmamk_f32 v101, v101, 0x3e38aa3b, v226
	v_fmamk_f32 v102, v102, 0x3e38aa3b, v226
	v_fmamk_f32 v103, v103, 0x3e38aa3b, v226
	v_fmamk_f32 v104, v104, 0x3e38aa3b, v226
	v_fmamk_f32 v105, v105, 0x3e38aa3b, v226
	v_exp_f32_e32 v98, v98
	v_exp_f32_e32 v99, v99
	v_exp_f32_e32 v100, v100
	v_exp_f32_e32 v101, v101
	v_exp_f32_e32 v102, v102
	v_exp_f32_e32 v103, v103
	v_exp_f32_e32 v104, v104
	v_exp_f32_e32 v105, v105
	v_add_f32_e32 v212, v98, v100
	v_add_f32_e32 v213, v99, v101
	v_add_f32_e32 v212, v212, v102
	v_add_f32_e32 v213, v213, v103
	v_add_f32_e32 v212, v212, v104
	v_add_f32_e32 v213, v213, v105
	v_cvt_pk_bf16_f32 v98, v98, v99
	v_cvt_pk_bf16_f32 v99, v100, v101
	v_cvt_pk_bf16_f32 v100, v102, v103
	v_cvt_pk_bf16_f32 v101, v104, v105
	s_waitcnt lgkmcnt(8)
	v_fmamk_f32 v106, v106, 0x3e38aa3b, v226
	v_fmamk_f32 v107, v107, 0x3e38aa3b, v226
	v_mfma_f32_32x32x16_bf16 v[50:65], v[130:133], v[98:101], v[50:65]
	v_fmamk_f32 v108, v108, 0x3e38aa3b, v226
	v_fmamk_f32 v109, v109, 0x3e38aa3b, v226
	v_fmamk_f32 v110, v110, 0x3e38aa3b, v226
	v_fmamk_f32 v111, v111, 0x3e38aa3b, v226
	v_fmamk_f32 v112, v112, 0x3e38aa3b, v226
	v_mfma_f32_32x32x16_bf16 v[34:49], v[134:137], v[98:101], v[34:49]
	v_fmamk_f32 v113, v113, 0x3e38aa3b, v226
	v_exp_f32_e32 v106, v106
	v_exp_f32_e32 v107, v107
	v_exp_f32_e32 v108, v108
	v_exp_f32_e32 v109, v109
	v_exp_f32_e32 v110, v110
	v_exp_f32_e32 v111, v111
	v_mfma_f32_32x32x16_bf16 v[18:33], v[138:141], v[98:101], v[18:33]
	v_exp_f32_e32 v112, v112
	v_exp_f32_e32 v113, v113
	v_add_f32_e32 v212, v212, v106
	v_add_f32_e32 v213, v213, v107
	v_add_f32_e32 v212, v212, v108
	v_add_f32_e32 v213, v213, v109
	v_add_f32_e32 v212, v212, v110
	v_add_f32_e32 v213, v213, v111
	v_add_f32_e32 v212, v212, v112
	v_add_f32_e32 v213, v213, v113
	v_cvt_pk_bf16_f32 v106, v106, v107
	v_mfma_f32_32x32x16_bf16 v[2:17], v[142:145], v[98:101], v[2:17]
	v_cvt_pk_bf16_f32 v107, v108, v109
	v_cvt_pk_bf16_f32 v108, v110, v111
	v_cvt_pk_bf16_f32 v109, v112, v113
	ds_read_b64_tr_b16 v[130:131], v228 offset:24576
	ds_read_b64_tr_b16 v[132:133], v229 offset:26624
	ds_read_b64_tr_b16 v[134:135], v230 offset:24576
	ds_read_b64_tr_b16 v[136:137], v231 offset:26624
	ds_read_b64_tr_b16 v[138:139], v232 offset:24576
	ds_read_b64_tr_b16 v[140:141], v233 offset:26624
	ds_read_b64_tr_b16 v[142:143], v234 offset:24576
	ds_read_b64_tr_b16 v[144:145], v235 offset:26624
	s_waitcnt lgkmcnt(8)
	v_mfma_f32_32x32x16_bf16 v[50:65], v[146:149], v[106:109], v[50:65]
	v_fmamk_f32 v82, v82, 0x3e38aa3b, v227
	v_fmamk_f32 v83, v83, 0x3e38aa3b, v227
	v_fmamk_f32 v84, v84, 0x3e38aa3b, v227
	v_fmamk_f32 v85, v85, 0x3e38aa3b, v227
	v_fmamk_f32 v86, v86, 0x3e38aa3b, v227
	v_fmamk_f32 v87, v87, 0x3e38aa3b, v227
	v_fmamk_f32 v88, v88, 0x3e38aa3b, v227
	v_mfma_f32_32x32x16_bf16 v[34:49], v[150:153], v[106:109], v[34:49]
	v_fmamk_f32 v89, v89, 0x3e38aa3b, v227
	v_exp_f32_e32 v82, v82
	v_exp_f32_e32 v83, v83
	v_exp_f32_e32 v84, v84
	v_exp_f32_e32 v85, v85
	v_exp_f32_e32 v86, v86
	v_exp_f32_e32 v87, v87
	v_mfma_f32_32x32x16_bf16 v[18:33], v[154:157], v[106:109], v[18:33]
	v_exp_f32_e32 v88, v88
	v_exp_f32_e32 v89, v89
	v_add_f32_e32 v212, v212, v82
	v_add_f32_e32 v213, v213, v83
	v_add_f32_e32 v212, v212, v84
	v_add_f32_e32 v213, v213, v85
	v_add_f32_e32 v212, v212, v86
	v_add_f32_e32 v213, v213, v87
	v_add_f32_e32 v212, v212, v88
	v_add_f32_e32 v213, v213, v89
	v_cvt_pk_bf16_f32 v82, v82, v83
	v_mfma_f32_32x32x16_bf16 v[2:17], v[158:161], v[106:109], v[2:17]
	v_cvt_pk_bf16_f32 v83, v84, v85
	v_cvt_pk_bf16_f32 v84, v86, v87
	v_cvt_pk_bf16_f32 v85, v88, v89
	ds_read_b64_tr_b16 v[146:147], v228 offset:28672
	ds_read_b64_tr_b16 v[148:149], v229 offset:30720
	ds_read_b64_tr_b16 v[150:151], v230 offset:28672
	ds_read_b64_tr_b16 v[152:153], v231 offset:30720
	ds_read_b64_tr_b16 v[154:155], v232 offset:28672
	ds_read_b64_tr_b16 v[156:157], v233 offset:30720
	ds_read_b64_tr_b16 v[158:159], v234 offset:28672
	ds_read_b64_tr_b16 v[160:161], v235 offset:30720
	s_waitcnt lgkmcnt(8)
	v_mfma_f32_32x32x16_bf16 v[50:65], v[130:133], v[82:85], v[50:65]
	v_fmamk_f32 v90, v90, 0x3e38aa3b, v227
	v_fmamk_f32 v91, v91, 0x3e38aa3b, v227
	v_fmamk_f32 v92, v92, 0x3e38aa3b, v227
	v_fmamk_f32 v93, v93, 0x3e38aa3b, v227
	v_fmamk_f32 v94, v94, 0x3e38aa3b, v227
	v_fmamk_f32 v95, v95, 0x3e38aa3b, v227
	v_fmamk_f32 v96, v96, 0x3e38aa3b, v227
	v_mfma_f32_32x32x16_bf16 v[34:49], v[134:137], v[82:85], v[34:49]
	v_fmamk_f32 v97, v97, 0x3e38aa3b, v227
	v_exp_f32_e32 v90, v90
	v_exp_f32_e32 v91, v91
	v_exp_f32_e32 v92, v92
	v_exp_f32_e32 v93, v93
	v_exp_f32_e32 v94, v94
	v_exp_f32_e32 v95, v95
	v_mfma_f32_32x32x16_bf16 v[18:33], v[138:141], v[82:85], v[18:33]
	v_exp_f32_e32 v96, v96
	v_exp_f32_e32 v97, v97
	v_add_f32_e32 v212, v212, v90
	v_add_f32_e32 v213, v213, v91
	v_add_f32_e32 v212, v212, v92
	v_add_f32_e32 v213, v213, v93
	v_add_f32_e32 v212, v212, v94
	v_add_f32_e32 v213, v213, v95
	v_add_f32_e32 v212, v212, v96
	v_add_f32_e32 v213, v213, v97
	v_cvt_pk_bf16_f32 v90, v90, v91
	v_mfma_f32_32x32x16_bf16 v[2:17], v[142:145], v[82:85], v[2:17]
	v_cvt_pk_bf16_f32 v91, v92, v93
	v_cvt_pk_bf16_f32 v92, v94, v95
	v_cvt_pk_bf16_f32 v93, v96, v97
	v_add_f32_e32 v212, v212, v213
	s_waitcnt lgkmcnt(0)
	v_add_f32_e32 v205, v205, v212
	v_mfma_f32_32x32x16_bf16 v[50:65], v[146:149], v[90:93], v[50:65]
	v_mfma_f32_32x32x16_bf16 v[34:49], v[150:153], v[90:93], v[34:49]
	v_mfma_f32_32x32x16_bf16 v[18:33], v[154:157], v[90:93], v[18:33]
	v_mfma_f32_32x32x16_bf16 v[2:17], v[158:161], v[90:93], v[2:17]
